# loop-edge edit: the 14 GEMM K-loop heads, the dilated slab loop head and the scan loop head aligned to 64 bytes with s_nop fill
# speedup vs baseline: 1.0012x; 1.0012x over previous
.LBB0_315:
	s_ashr_i32 s19, s18, 31
	v_cmp_lt_i64_e32 vcc, s[34:35], v[144:145]
	s_lshl_b64 s[34:35], s[18:19], 19
	s_add_u32 s34, s64, s34
	s_addc_u32 s35, s65, s35
	s_and_b64 s[36:37], vcc, exec
	s_cselect_b32 s19, s35, s59
	s_cselect_b32 s94, s34, s58
	s_ashr_i32 s15, s14, 31
	s_lshl_b64 s[36:37], s[14:15], 19
	s_add_u32 s36, s2, s36
	s_addc_u32 s37, s3, s37
	s_and_b64 s[60:61], vcc, exec
	s_cselect_b32 s15, s37, s57
	s_cselect_b32 s95, s36, s56
	s_add_u32 s96, s56, 0x100
	s_addc_u32 s97, s57, 0
	s_add_u32 s56, s58, 0x40080
	v_mov_b32_e32 v0, 0
	s_addc_u32 s57, s59, 0
	s_mov_b32 vcc_lo, -2
	v_mov_b32_e32 v1, v0
	v_mov_b32_e32 v2, v0
	v_mov_b32_e32 v3, v0
	v_mov_b32_e32 v4, v0
	v_mov_b32_e32 v5, v0
	v_mov_b32_e32 v6, v0
	v_mov_b32_e32 v7, v0
	v_mov_b32_e32 v16, v0
	v_mov_b32_e32 v17, v0
	v_mov_b32_e32 v18, v0
	v_mov_b32_e32 v19, v0
	v_mov_b32_e32 v20, v0
	v_mov_b32_e32 v21, v0
	v_mov_b32_e32 v22, v0
	v_mov_b32_e32 v23, v0
	v_mov_b32_e32 v32, v0
	v_mov_b32_e32 v33, v0
	v_mov_b32_e32 v34, v0
	v_mov_b32_e32 v35, v0
	v_mov_b32_e32 v36, v0
	v_mov_b32_e32 v37, v0
	v_mov_b32_e32 v38, v0
	v_mov_b32_e32 v39, v0
	v_mov_b32_e32 v48, v0
	v_mov_b32_e32 v49, v0
	v_mov_b32_e32 v50, v0
	v_mov_b32_e32 v51, v0
	v_mov_b32_e32 v52, v0
	v_mov_b32_e32 v53, v0
	v_mov_b32_e32 v54, v0
	v_mov_b32_e32 v55, v0
	v_mov_b32_e32 v8, v0
	v_mov_b32_e32 v9, v0
	v_mov_b32_e32 v10, v0
	v_mov_b32_e32 v11, v0
	v_mov_b32_e32 v12, v0
	v_mov_b32_e32 v13, v0
	v_mov_b32_e32 v14, v0
	v_mov_b32_e32 v15, v0
	v_mov_b32_e32 v24, v0
	v_mov_b32_e32 v25, v0
	v_mov_b32_e32 v26, v0
	v_mov_b32_e32 v27, v0
	v_mov_b32_e32 v28, v0
	v_mov_b32_e32 v29, v0
	v_mov_b32_e32 v30, v0
	v_mov_b32_e32 v31, v0
	v_mov_b32_e32 v40, v0
	v_mov_b32_e32 v41, v0
	v_mov_b32_e32 v42, v0
	v_mov_b32_e32 v43, v0
	v_mov_b32_e32 v44, v0
	v_mov_b32_e32 v45, v0
	v_mov_b32_e32 v46, v0
	v_mov_b32_e32 v47, v0
	v_mov_b32_e32 v56, v0
	v_mov_b32_e32 v57, v0
	v_mov_b32_e32 v58, v0
	v_mov_b32_e32 v59, v0
	v_mov_b32_e32 v60, v0
	v_mov_b32_e32 v61, v0
	v_mov_b32_e32 v62, v0
	v_mov_b32_e32 v63, v0
	v_mov_b32_e32 v64, v0
	v_mov_b32_e32 v65, v0
	v_mov_b32_e32 v66, v0
	v_mov_b32_e32 v67, v0
	v_mov_b32_e32 v68, v0
	v_mov_b32_e32 v69, v0
	v_mov_b32_e32 v70, v0
	v_mov_b32_e32 v71, v0
	v_mov_b32_e32 v80, v0
	v_mov_b32_e32 v81, v0
	v_mov_b32_e32 v82, v0
	v_mov_b32_e32 v83, v0
	v_mov_b32_e32 v84, v0
	v_mov_b32_e32 v85, v0
	v_mov_b32_e32 v86, v0
	v_mov_b32_e32 v87, v0
	v_mov_b32_e32 v96, v0
	v_mov_b32_e32 v97, v0
	v_mov_b32_e32 v98, v0
	v_mov_b32_e32 v99, v0
	v_mov_b32_e32 v100, v0
	v_mov_b32_e32 v101, v0
	v_mov_b32_e32 v102, v0
	v_mov_b32_e32 v103, v0
	v_mov_b32_e32 v112, v0
	v_mov_b32_e32 v113, v0
	v_mov_b32_e32 v114, v0
	v_mov_b32_e32 v115, v0
	v_mov_b32_e32 v116, v0
	v_mov_b32_e32 v117, v0
	v_mov_b32_e32 v118, v0
	v_mov_b32_e32 v119, v0
	v_mov_b32_e32 v72, v0
	v_mov_b32_e32 v73, v0
	v_mov_b32_e32 v74, v0
	v_mov_b32_e32 v75, v0
	v_mov_b32_e32 v76, v0
	v_mov_b32_e32 v77, v0
	v_mov_b32_e32 v78, v0
	v_mov_b32_e32 v79, v0
	v_mov_b32_e32 v88, v0
	v_mov_b32_e32 v89, v0
	v_mov_b32_e32 v90, v0
	v_mov_b32_e32 v91, v0
	v_mov_b32_e32 v92, v0
	v_mov_b32_e32 v93, v0
	v_mov_b32_e32 v94, v0
	v_mov_b32_e32 v95, v0
	v_mov_b32_e32 v104, v0
	v_mov_b32_e32 v105, v0
	v_mov_b32_e32 v106, v0
	v_mov_b32_e32 v107, v0
	v_mov_b32_e32 v108, v0
	v_mov_b32_e32 v109, v0
	v_mov_b32_e32 v110, v0
	v_mov_b32_e32 v111, v0
	v_mov_b32_e32 v120, v0
	v_mov_b32_e32 v121, v0
	v_mov_b32_e32 v122, v0
	v_mov_b32_e32 v123, v0
	v_mov_b32_e32 v124, v0
	v_mov_b32_e32 v125, v0
	v_mov_b32_e32 v126, v0
	v_mov_b32_e32 v127, v0
	.p2alignl 6, 3212836864

.LBB0_396:
	s_add_u32 s37, s38, 0x100
	s_addc_u32 s18, s39, 0
	s_add_u32 s16, s56, 0xb0080
	v_mov_b32_e32 v0, 0
	s_addc_u32 s17, s57, 0
	s_mov_b32 s19, -2
	s_waitcnt lgkmcnt(0)
	v_mov_b32_e32 v1, v0
	v_mov_b32_e32 v2, v0
	v_mov_b32_e32 v3, v0
	v_mov_b32_e32 v4, v0
	v_mov_b32_e32 v5, v0
	v_mov_b32_e32 v6, v0
	v_mov_b32_e32 v7, v0
	v_mov_b32_e32 v16, v0
	v_mov_b32_e32 v17, v0
	v_mov_b32_e32 v18, v0
	v_mov_b32_e32 v19, v0
	v_mov_b32_e32 v20, v0
	v_mov_b32_e32 v21, v0
	v_mov_b32_e32 v22, v0
	v_mov_b32_e32 v23, v0
	v_mov_b32_e32 v32, v0
	v_mov_b32_e32 v33, v0
	v_mov_b32_e32 v34, v0
	v_mov_b32_e32 v35, v0
	v_mov_b32_e32 v36, v0
	v_mov_b32_e32 v37, v0
	v_mov_b32_e32 v38, v0
	v_mov_b32_e32 v39, v0
	v_mov_b32_e32 v48, v0
	v_mov_b32_e32 v49, v0
	v_mov_b32_e32 v50, v0
	v_mov_b32_e32 v51, v0
	v_mov_b32_e32 v52, v0
	v_mov_b32_e32 v53, v0
	v_mov_b32_e32 v54, v0
	v_mov_b32_e32 v55, v0
	v_mov_b32_e32 v8, v0
	v_mov_b32_e32 v9, v0
	v_mov_b32_e32 v10, v0
	v_mov_b32_e32 v11, v0
	v_mov_b32_e32 v12, v0
	v_mov_b32_e32 v13, v0
	v_mov_b32_e32 v14, v0
	v_mov_b32_e32 v15, v0
	v_mov_b32_e32 v24, v0
	v_mov_b32_e32 v25, v0
	v_mov_b32_e32 v26, v0
	v_mov_b32_e32 v27, v0
	v_mov_b32_e32 v28, v0
	v_mov_b32_e32 v29, v0
	v_mov_b32_e32 v30, v0
	v_mov_b32_e32 v31, v0
	v_mov_b32_e32 v40, v0
	v_mov_b32_e32 v41, v0
	v_mov_b32_e32 v42, v0
	v_mov_b32_e32 v43, v0
	v_mov_b32_e32 v44, v0
	v_mov_b32_e32 v45, v0
	v_mov_b32_e32 v46, v0
	v_mov_b32_e32 v47, v0
	v_mov_b32_e32 v56, v0
	v_mov_b32_e32 v57, v0
	v_mov_b32_e32 v58, v0
	v_mov_b32_e32 v59, v0
	v_mov_b32_e32 v60, v0
	v_mov_b32_e32 v61, v0
	v_mov_b32_e32 v62, v0
	v_mov_b32_e32 v63, v0
	v_mov_b32_e32 v64, v0
	v_mov_b32_e32 v65, v0
	v_mov_b32_e32 v66, v0
	v_mov_b32_e32 v67, v0
	v_mov_b32_e32 v68, v0
	v_mov_b32_e32 v69, v0
	v_mov_b32_e32 v70, v0
	v_mov_b32_e32 v71, v0
	v_mov_b32_e32 v80, v0
	v_mov_b32_e32 v81, v0
	v_mov_b32_e32 v82, v0
	v_mov_b32_e32 v83, v0
	v_mov_b32_e32 v84, v0
	v_mov_b32_e32 v85, v0
	v_mov_b32_e32 v86, v0
	v_mov_b32_e32 v87, v0
	v_mov_b32_e32 v96, v0
	v_mov_b32_e32 v97, v0
	v_mov_b32_e32 v98, v0
	v_mov_b32_e32 v99, v0
	v_mov_b32_e32 v100, v0
	v_mov_b32_e32 v101, v0
	v_mov_b32_e32 v102, v0
	v_mov_b32_e32 v103, v0
	v_mov_b32_e32 v112, v0
	v_mov_b32_e32 v113, v0
	v_mov_b32_e32 v114, v0
	v_mov_b32_e32 v115, v0
	v_mov_b32_e32 v116, v0
	v_mov_b32_e32 v117, v0
	v_mov_b32_e32 v118, v0
	v_mov_b32_e32 v119, v0
	v_mov_b32_e32 v72, v0
	v_mov_b32_e32 v73, v0
	v_mov_b32_e32 v74, v0
	v_mov_b32_e32 v75, v0
	v_mov_b32_e32 v76, v0
	v_mov_b32_e32 v77, v0
	v_mov_b32_e32 v78, v0
	v_mov_b32_e32 v79, v0
	v_mov_b32_e32 v88, v0
	v_mov_b32_e32 v89, v0
	v_mov_b32_e32 v90, v0
	v_mov_b32_e32 v91, v0
	v_mov_b32_e32 v92, v0
	v_mov_b32_e32 v93, v0
	v_mov_b32_e32 v94, v0
	v_mov_b32_e32 v95, v0
	v_mov_b32_e32 v104, v0
	v_mov_b32_e32 v105, v0
	v_mov_b32_e32 v106, v0
	v_mov_b32_e32 v107, v0
	v_mov_b32_e32 v108, v0
	v_mov_b32_e32 v109, v0
	v_mov_b32_e32 v110, v0
	v_mov_b32_e32 v111, v0
	v_mov_b32_e32 v120, v0
	v_mov_b32_e32 v121, v0
	v_mov_b32_e32 v122, v0
	v_mov_b32_e32 v123, v0
	v_mov_b32_e32 v124, v0
	v_mov_b32_e32 v125, v0
	v_mov_b32_e32 v126, v0
	v_mov_b32_e32 v127, v0
	.p2alignl 6, 3212836864

.LBB0_431:
	s_ashr_i32 s7, s6, 31
	v_cmp_lt_i64_e64 s[18:19], s[10:11], 4
	s_lshl_b64 s[10:11], s[6:7], 19
	s_add_u32 s10, s56, s10
	s_addc_u32 s11, s57, s11
	s_and_b64 s[12:13], s[18:19], exec
	s_cselect_b32 s7, s11, s37
	s_cselect_b32 vcc_lo, s10, s36
	s_ashr_i32 s5, s4, 31
	s_lshl_b64 s[12:13], s[4:5], 19
	s_add_u32 s12, s63, s12
	s_addc_u32 s13, s64, s13
	s_and_b64 s[18:19], s[18:19], exec
	s_cselect_b32 s5, s13, s17
	s_cselect_b32 vcc_hi, s12, s16
	s_add_u32 s18, s16, 0x100
	s_addc_u32 s19, s17, 0
	s_add_u32 s16, s36, 0x40080
	v_mov_b32_e32 v0, 0
	s_addc_u32 s17, s37, 0
	s_mov_b32 s33, -2
	v_mov_b32_e32 v1, v0
	v_mov_b32_e32 v2, v0
	v_mov_b32_e32 v3, v0
	v_mov_b32_e32 v4, v0
	v_mov_b32_e32 v5, v0
	v_mov_b32_e32 v6, v0
	v_mov_b32_e32 v7, v0
	v_mov_b32_e32 v16, v0
	v_mov_b32_e32 v17, v0
	v_mov_b32_e32 v18, v0
	v_mov_b32_e32 v19, v0
	v_mov_b32_e32 v20, v0
	v_mov_b32_e32 v21, v0
	v_mov_b32_e32 v22, v0
	v_mov_b32_e32 v23, v0
	v_mov_b32_e32 v32, v0
	v_mov_b32_e32 v33, v0
	v_mov_b32_e32 v34, v0
	v_mov_b32_e32 v35, v0
	v_mov_b32_e32 v36, v0
	v_mov_b32_e32 v37, v0
	v_mov_b32_e32 v38, v0
	v_mov_b32_e32 v39, v0
	v_mov_b32_e32 v48, v0
	v_mov_b32_e32 v49, v0
	v_mov_b32_e32 v50, v0
	v_mov_b32_e32 v51, v0
	v_mov_b32_e32 v52, v0
	v_mov_b32_e32 v53, v0
	v_mov_b32_e32 v54, v0
	v_mov_b32_e32 v55, v0
	v_mov_b32_e32 v8, v0
	v_mov_b32_e32 v9, v0
	v_mov_b32_e32 v10, v0
	v_mov_b32_e32 v11, v0
	v_mov_b32_e32 v12, v0
	v_mov_b32_e32 v13, v0
	v_mov_b32_e32 v14, v0
	v_mov_b32_e32 v15, v0
	v_mov_b32_e32 v24, v0
	v_mov_b32_e32 v25, v0
	v_mov_b32_e32 v26, v0
	v_mov_b32_e32 v27, v0
	v_mov_b32_e32 v28, v0
	v_mov_b32_e32 v29, v0
	v_mov_b32_e32 v30, v0
	v_mov_b32_e32 v31, v0
	v_mov_b32_e32 v40, v0
	v_mov_b32_e32 v41, v0
	v_mov_b32_e32 v42, v0
	v_mov_b32_e32 v43, v0
	v_mov_b32_e32 v44, v0
	v_mov_b32_e32 v45, v0
	v_mov_b32_e32 v46, v0
	v_mov_b32_e32 v47, v0
	v_mov_b32_e32 v56, v0
	v_mov_b32_e32 v57, v0
	v_mov_b32_e32 v58, v0
	v_mov_b32_e32 v59, v0
	v_mov_b32_e32 v60, v0
	v_mov_b32_e32 v61, v0
	v_mov_b32_e32 v62, v0
	v_mov_b32_e32 v63, v0
	v_mov_b32_e32 v64, v0
	v_mov_b32_e32 v65, v0
	v_mov_b32_e32 v66, v0
	v_mov_b32_e32 v67, v0
	v_mov_b32_e32 v68, v0
	v_mov_b32_e32 v69, v0
	v_mov_b32_e32 v70, v0
	v_mov_b32_e32 v71, v0
	v_mov_b32_e32 v80, v0
	v_mov_b32_e32 v81, v0
	v_mov_b32_e32 v82, v0
	v_mov_b32_e32 v83, v0
	v_mov_b32_e32 v84, v0
	v_mov_b32_e32 v85, v0
	v_mov_b32_e32 v86, v0
	v_mov_b32_e32 v87, v0
	v_mov_b32_e32 v96, v0
	v_mov_b32_e32 v97, v0
	v_mov_b32_e32 v98, v0
	v_mov_b32_e32 v99, v0
	v_mov_b32_e32 v100, v0
	v_mov_b32_e32 v101, v0
	v_mov_b32_e32 v102, v0
	v_mov_b32_e32 v103, v0
	v_mov_b32_e32 v128, v0
	v_mov_b32_e32 v129, v0
	v_mov_b32_e32 v130, v0
	v_mov_b32_e32 v131, v0
	v_mov_b32_e32 v132, v0
	v_mov_b32_e32 v133, v0
	v_mov_b32_e32 v134, v0
	v_mov_b32_e32 v135, v0
	v_mov_b32_e32 v72, v0
	v_mov_b32_e32 v73, v0
	v_mov_b32_e32 v74, v0
	v_mov_b32_e32 v75, v0
	v_mov_b32_e32 v76, v0
	v_mov_b32_e32 v77, v0
	v_mov_b32_e32 v78, v0
	v_mov_b32_e32 v79, v0
	v_mov_b32_e32 v88, v0
	v_mov_b32_e32 v89, v0
	v_mov_b32_e32 v90, v0
	v_mov_b32_e32 v91, v0
	v_mov_b32_e32 v92, v0
	v_mov_b32_e32 v93, v0
	v_mov_b32_e32 v94, v0
	v_mov_b32_e32 v95, v0
	v_mov_b32_e32 v104, v0
	v_mov_b32_e32 v105, v0
	v_mov_b32_e32 v106, v0
	v_mov_b32_e32 v107, v0
	v_mov_b32_e32 v108, v0
	v_mov_b32_e32 v109, v0
	v_mov_b32_e32 v110, v0
	v_mov_b32_e32 v111, v0
	v_mov_b32_e32 v136, v0
	v_mov_b32_e32 v137, v0
	v_mov_b32_e32 v138, v0
	v_mov_b32_e32 v139, v0
	v_mov_b32_e32 v140, v0
	v_mov_b32_e32 v141, v0
	v_mov_b32_e32 v142, v0
	v_mov_b32_e32 v143, v0
	.p2alignl 6, 3212836864

.LBB0_453:
	s_ashr_i32 s7, s6, 31
	v_cmp_lt_i64_e64 s[18:19], s[8:9], 4
	s_lshl_b64 s[8:9], s[6:7], 19
	s_add_u32 s8, s56, s8
	s_addc_u32 s9, s57, s9
	s_and_b64 s[10:11], s[18:19], exec
	s_cselect_b32 s7, s9, s17
	s_cselect_b32 s94, s8, s16
	s_ashr_i32 s5, s4, 31
	s_lshl_b64 s[10:11], s[4:5], 19
	s_add_u32 s10, s39, s10
	s_addc_u32 s11, s60, s11
	s_and_b64 s[18:19], s[18:19], exec
	s_cselect_b32 s5, s11, s15
	s_cselect_b32 s95, s10, s14
	s_add_u32 s18, s14, 0x100
	s_addc_u32 s19, s15, 0
	s_add_u32 s14, s16, 0x40080
	v_mov_b32_e32 v0, 0
	s_addc_u32 s15, s17, 0
	s_mov_b32 s96, -2
	v_mov_b32_e32 v1, v0
	v_mov_b32_e32 v2, v0
	v_mov_b32_e32 v3, v0
	v_mov_b32_e32 v4, v0
	v_mov_b32_e32 v5, v0
	v_mov_b32_e32 v6, v0
	v_mov_b32_e32 v7, v0
	v_mov_b32_e32 v16, v0
	v_mov_b32_e32 v17, v0
	v_mov_b32_e32 v18, v0
	v_mov_b32_e32 v19, v0
	v_mov_b32_e32 v20, v0
	v_mov_b32_e32 v21, v0
	v_mov_b32_e32 v22, v0
	v_mov_b32_e32 v23, v0
	v_mov_b32_e32 v32, v0
	v_mov_b32_e32 v33, v0
	v_mov_b32_e32 v34, v0
	v_mov_b32_e32 v35, v0
	v_mov_b32_e32 v36, v0
	v_mov_b32_e32 v37, v0
	v_mov_b32_e32 v38, v0
	v_mov_b32_e32 v39, v0
	v_mov_b32_e32 v48, v0
	v_mov_b32_e32 v49, v0
	v_mov_b32_e32 v50, v0
	v_mov_b32_e32 v51, v0
	v_mov_b32_e32 v52, v0
	v_mov_b32_e32 v53, v0
	v_mov_b32_e32 v54, v0
	v_mov_b32_e32 v55, v0
	v_mov_b32_e32 v8, v0
	v_mov_b32_e32 v9, v0
	v_mov_b32_e32 v10, v0
	v_mov_b32_e32 v11, v0
	v_mov_b32_e32 v12, v0
	v_mov_b32_e32 v13, v0
	v_mov_b32_e32 v14, v0
	v_mov_b32_e32 v15, v0
	v_mov_b32_e32 v24, v0
	v_mov_b32_e32 v25, v0
	v_mov_b32_e32 v26, v0
	v_mov_b32_e32 v27, v0
	v_mov_b32_e32 v28, v0
	v_mov_b32_e32 v29, v0
	v_mov_b32_e32 v30, v0
	v_mov_b32_e32 v31, v0
	v_mov_b32_e32 v40, v0
	v_mov_b32_e32 v41, v0
	v_mov_b32_e32 v42, v0
	v_mov_b32_e32 v43, v0
	v_mov_b32_e32 v44, v0
	v_mov_b32_e32 v45, v0
	v_mov_b32_e32 v46, v0
	v_mov_b32_e32 v47, v0
	v_mov_b32_e32 v56, v0
	v_mov_b32_e32 v57, v0
	v_mov_b32_e32 v58, v0
	v_mov_b32_e32 v59, v0
	v_mov_b32_e32 v60, v0
	v_mov_b32_e32 v61, v0
	v_mov_b32_e32 v62, v0
	v_mov_b32_e32 v63, v0
	v_mov_b32_e32 v64, v0
	v_mov_b32_e32 v65, v0
	v_mov_b32_e32 v66, v0
	v_mov_b32_e32 v67, v0
	v_mov_b32_e32 v68, v0
	v_mov_b32_e32 v69, v0
	v_mov_b32_e32 v70, v0
	v_mov_b32_e32 v71, v0
	v_mov_b32_e32 v80, v0
	v_mov_b32_e32 v81, v0
	v_mov_b32_e32 v82, v0
	v_mov_b32_e32 v83, v0
	v_mov_b32_e32 v84, v0
	v_mov_b32_e32 v85, v0
	v_mov_b32_e32 v86, v0
	v_mov_b32_e32 v87, v0
	v_mov_b32_e32 v96, v0
	v_mov_b32_e32 v97, v0
	v_mov_b32_e32 v98, v0
	v_mov_b32_e32 v99, v0
	v_mov_b32_e32 v100, v0
	v_mov_b32_e32 v101, v0
	v_mov_b32_e32 v102, v0
	v_mov_b32_e32 v103, v0
	v_mov_b32_e32 v128, v0
	v_mov_b32_e32 v129, v0
	v_mov_b32_e32 v130, v0
	v_mov_b32_e32 v131, v0
	v_mov_b32_e32 v132, v0
	v_mov_b32_e32 v133, v0
	v_mov_b32_e32 v134, v0
	v_mov_b32_e32 v135, v0
	v_mov_b32_e32 v72, v0
	v_mov_b32_e32 v73, v0
	v_mov_b32_e32 v74, v0
	v_mov_b32_e32 v75, v0
	v_mov_b32_e32 v76, v0
	v_mov_b32_e32 v77, v0
	v_mov_b32_e32 v78, v0
	v_mov_b32_e32 v79, v0
	v_mov_b32_e32 v88, v0
	v_mov_b32_e32 v89, v0
	v_mov_b32_e32 v90, v0
	v_mov_b32_e32 v91, v0
	v_mov_b32_e32 v92, v0
	v_mov_b32_e32 v93, v0
	v_mov_b32_e32 v94, v0
	v_mov_b32_e32 v95, v0
	v_mov_b32_e32 v104, v0
	v_mov_b32_e32 v105, v0
	v_mov_b32_e32 v106, v0
	v_mov_b32_e32 v107, v0
	v_mov_b32_e32 v108, v0
	v_mov_b32_e32 v109, v0
	v_mov_b32_e32 v110, v0
	v_mov_b32_e32 v111, v0
	v_mov_b32_e32 v136, v0
	v_mov_b32_e32 v137, v0
	v_mov_b32_e32 v138, v0
	v_mov_b32_e32 v139, v0
	v_mov_b32_e32 v140, v0
	v_mov_b32_e32 v141, v0
	v_mov_b32_e32 v142, v0
	v_mov_b32_e32 v143, v0
	.p2alignl 6, 3212836864

.LBB0_525:
	s_ashr_i32 s17, s16, 31
	v_cmp_lt_i64_e32 vcc, s[18:19], v[150:151]
	s_lshl_b64 s[18:19], s[16:17], 19
	s_add_u32 s18, s64, s18
	s_addc_u32 s19, s65, s19
	s_and_b64 s[20:21], vcc, exec
	s_cselect_b32 s17, s19, s57
	s_cselect_b32 s37, s18, s56
	s_ashr_i32 s15, s14, 31
	s_lshl_b64 s[20:21], s[14:15], 19
	s_add_u32 s34, s61, s20
	s_addc_u32 s35, s62, s21
	s_and_b64 s[20:21], vcc, exec
	s_cselect_b32 s15, s35, s39
	s_cselect_b32 vcc_lo, s34, s38
	s_add_u32 vcc_hi, s38, 0x100
	s_addc_u32 s33, s39, 0
	s_add_u32 s38, s56, 0x40080
	v_mov_b32_e32 v0, 0
	s_addc_u32 s39, s57, 0
	s_mov_b32 s66, -2
	v_mov_b32_e32 v1, v0
	v_mov_b32_e32 v2, v0
	v_mov_b32_e32 v3, v0
	v_mov_b32_e32 v4, v0
	v_mov_b32_e32 v5, v0
	v_mov_b32_e32 v6, v0
	v_mov_b32_e32 v7, v0
	v_mov_b32_e32 v12, v0
	v_mov_b32_e32 v13, v0
	v_mov_b32_e32 v14, v0
	v_mov_b32_e32 v15, v0
	v_mov_b32_e32 v20, v0
	v_mov_b32_e32 v21, v0
	v_mov_b32_e32 v22, v0
	v_mov_b32_e32 v23, v0
	v_mov_b32_e32 v28, v0
	v_mov_b32_e32 v29, v0
	v_mov_b32_e32 v30, v0
	v_mov_b32_e32 v31, v0
	v_mov_b32_e32 v36, v0
	v_mov_b32_e32 v37, v0
	v_mov_b32_e32 v38, v0
	v_mov_b32_e32 v39, v0
	v_mov_b32_e32 v44, v0
	v_mov_b32_e32 v45, v0
	v_mov_b32_e32 v46, v0
	v_mov_b32_e32 v47, v0
	v_mov_b32_e32 v52, v0
	v_mov_b32_e32 v53, v0
	v_mov_b32_e32 v54, v0
	v_mov_b32_e32 v55, v0
	v_mov_b32_e32 v8, v0
	v_mov_b32_e32 v9, v0
	v_mov_b32_e32 v10, v0
	v_mov_b32_e32 v11, v0
	v_mov_b32_e32 v16, v0
	v_mov_b32_e32 v17, v0
	v_mov_b32_e32 v18, v0
	v_mov_b32_e32 v19, v0
	v_mov_b32_e32 v24, v0
	v_mov_b32_e32 v25, v0
	v_mov_b32_e32 v26, v0
	v_mov_b32_e32 v27, v0
	v_mov_b32_e32 v32, v0
	v_mov_b32_e32 v33, v0
	v_mov_b32_e32 v34, v0
	v_mov_b32_e32 v35, v0
	v_mov_b32_e32 v40, v0
	v_mov_b32_e32 v41, v0
	v_mov_b32_e32 v42, v0
	v_mov_b32_e32 v43, v0
	v_mov_b32_e32 v48, v0
	v_mov_b32_e32 v49, v0
	v_mov_b32_e32 v50, v0
	v_mov_b32_e32 v51, v0
	v_mov_b32_e32 v56, v0
	v_mov_b32_e32 v57, v0
	v_mov_b32_e32 v58, v0
	v_mov_b32_e32 v59, v0
	v_mov_b32_e32 v60, v0
	v_mov_b32_e32 v61, v0
	v_mov_b32_e32 v62, v0
	v_mov_b32_e32 v63, v0
	v_mov_b32_e32 v64, v0
	v_mov_b32_e32 v65, v0
	v_mov_b32_e32 v66, v0
	v_mov_b32_e32 v67, v0
	v_mov_b32_e32 v68, v0
	v_mov_b32_e32 v69, v0
	v_mov_b32_e32 v70, v0
	v_mov_b32_e32 v71, v0
	v_mov_b32_e32 v76, v0
	v_mov_b32_e32 v77, v0
	v_mov_b32_e32 v78, v0
	v_mov_b32_e32 v79, v0
	v_mov_b32_e32 v84, v0
	v_mov_b32_e32 v85, v0
	v_mov_b32_e32 v86, v0
	v_mov_b32_e32 v87, v0
	v_mov_b32_e32 v92, v0
	v_mov_b32_e32 v93, v0
	v_mov_b32_e32 v94, v0
	v_mov_b32_e32 v95, v0
	v_mov_b32_e32 v100, v0
	v_mov_b32_e32 v101, v0
	v_mov_b32_e32 v102, v0
	v_mov_b32_e32 v103, v0
	v_mov_b32_e32 v108, v0
	v_mov_b32_e32 v109, v0
	v_mov_b32_e32 v110, v0
	v_mov_b32_e32 v111, v0
	v_mov_b32_e32 v116, v0
	v_mov_b32_e32 v117, v0
	v_mov_b32_e32 v118, v0
	v_mov_b32_e32 v119, v0
	v_mov_b32_e32 v72, v0
	v_mov_b32_e32 v73, v0
	v_mov_b32_e32 v74, v0
	v_mov_b32_e32 v75, v0
	v_mov_b32_e32 v80, v0
	v_mov_b32_e32 v81, v0
	v_mov_b32_e32 v82, v0
	v_mov_b32_e32 v83, v0
	v_mov_b32_e32 v88, v0
	v_mov_b32_e32 v89, v0
	v_mov_b32_e32 v90, v0
	v_mov_b32_e32 v91, v0
	v_mov_b32_e32 v96, v0
	v_mov_b32_e32 v97, v0
	v_mov_b32_e32 v98, v0
	v_mov_b32_e32 v99, v0
	v_mov_b32_e32 v104, v0
	v_mov_b32_e32 v105, v0
	v_mov_b32_e32 v106, v0
	v_mov_b32_e32 v107, v0
	v_mov_b32_e32 v112, v0
	v_mov_b32_e32 v113, v0
	v_mov_b32_e32 v114, v0
	v_mov_b32_e32 v115, v0
	v_mov_b32_e32 v120, v0
	v_mov_b32_e32 v121, v0
	v_mov_b32_e32 v122, v0
	v_mov_b32_e32 v123, v0
	v_mov_b32_e32 v124, v0
	v_mov_b32_e32 v125, v0
	v_mov_b32_e32 v126, v0
	v_mov_b32_e32 v127, v0
	.p2alignl 6, 3212836864

.LBB0_703:
	s_or_b64 exec, exec, s[10:11]
	s_movk_i32 s10, 0xffcc
	v_mad_u64_u32 v[0:1], s[10:11], v200, s10, v[0:1]
	v_ashrrev_i32_e32 v1, 2, v0
	v_lshlrev_b32_e32 v202, 4, v1
	v_cmp_gt_i32_e32 vcc, 12, v1
	v_mad_i64_i32 v[2:3], s[10:11], v200, s56, 0
	s_nop 0
	v_cndmask_b32_e32 v4, 0, v202, vcc
	v_ashrrev_i32_e32 v5, 31, v4
	v_mad_i64_i32 v[4:5], s[10:11], v200, s56, v[4:5]
	v_or_b32_e32 v4, v4, v180
	v_or_b32_e32 v2, v2, v192
	v_ashrrev_i32_e32 v201, 31, v200
	v_lshlrev_b64 v[4:5], 8, v[4:5]
	v_lshlrev_b64 v[2:3], 8, v[2:3]
	v_lshlrev_b64 v[6:7], 15, v[200:201]
	v_lshl_add_u64 v[220:221], v[184:185], 0, v[4:5]
	v_lshl_add_u64 v[222:223], v[186:187], 0, v[2:3]
	v_lshl_add_u64 v[224:225], v[188:189], 0, v[6:7]
	v_mad_i64_i32 v[2:3], s[10:11], v218, s57, v[220:221]
	v_mad_i64_i32 v[6:7], s[10:11], v218, s57, v[222:223]
	s_movk_i32 s10, 0x1000
	s_nop 0
	v_add_co_u32_e32 v8, vcc, s10, v6
	v_ashrrev_i32_e32 v219, 31, v218
	s_nop 0
	v_addc_co_u32_e32 v9, vcc, 0, v7, vcc
	s_movk_i32 s10, 0x2000
	v_lshlrev_b64 v[4:5], 8, v[218:219]
	v_add_co_u32_e32 v10, vcc, s10, v6
	v_lshl_add_u64 v[4:5], v[224:225], 0, v[4:5]
	s_nop 0
	v_addc_co_u32_e32 v11, vcc, 0, v7, vcc
	s_waitcnt vmcnt(0)
	global_load_dwordx4 v[144:147], v[2:3], off
	global_load_dwordx4 v[120:123], v[2:3], off offset:64
	global_load_dwordx4 v[152:155], v[4:5], off
	global_load_dwordx4 v[128:131], v[4:5], off offset:64
	global_load_dwordx4 v[140:143], v[6:7], off
	global_load_dwordx4 v[108:111], v[6:7], off offset:64
	global_load_dwordx4 v[148:151], v[8:9], off
	global_load_dwordx4 v[124:127], v[8:9], off offset:64
	global_load_dwordx4 v[156:159], v[10:11], off
	global_load_dwordx4 v[136:139], v[10:11], off offset:64
	global_load_dwordx4 v[92:95], v[2:3], off offset:128
	global_load_dwordx4 v[72:75], v[2:3], off offset:192
	global_load_dwordx4 v[116:119], v[4:5], off offset:128
	global_load_dwordx4 v[76:79], v[4:5], off offset:192
	global_load_dwordx4 v[104:107], v[6:7], off offset:128
	global_load_dwordx4 v[60:63], v[6:7], off offset:192
	global_load_dwordx4 v[112:115], v[8:9], off offset:128
	global_load_dwordx4 v[56:59], v[8:9], off offset:192
	global_load_dwordx4 v[132:135], v[10:11], off offset:128
	global_load_dwordx4 v[48:51], v[10:11], off offset:192
	v_add_u32_e32 v2, v216, v218
	v_ashrrev_i32_e32 v3, 31, v2
	v_lshlrev_b64 v[226:227], 2, v[2:3]
	v_lshl_add_u64 v[2:3], s[4:5], 0, v[226:227]
	v_lshl_add_u64 v[4:5], s[2:3], 0, v[226:227]
	global_load_dword v234, v[2:3], off
	global_load_dword v235, v[4:5], off
	s_movk_i32 s10, 0x6800
	v_mad_i64_i32 v[228:229], s[10:11], v200, s10, 0
	v_or_b32_e32 v0, v0, v178
	v_ashrrev_i32_e32 v203, 31, v202
	v_cmp_eq_u32_e64 s[14:15], 0, v0
	v_add_u32_e32 v0, 0x19f, v191
	v_or_b32_e32 v2, v190, v228
	v_mov_b32_e32 v3, v229
	v_cmp_lt_i32_e64 s[12:13], 11, v1
	s_waitcnt vmcnt(0)
	v_cmp_gt_u32_e64 s[10:11], s58, v0
	v_mad_i64_i32 v[0:1], s[20:21], v218, s59, v[198:199]
	v_lshl_add_u64 v[2:3], v[2:3], 0, v[202:203]
	v_mad_u64_u32 v[230:231], s[20:21], v2, s60, v[0:1]
	s_mov_b32 s65, 0
	v_or_b32_e32 v233, 63, v218
	v_mad_i32_i24 v231, v3, s60, v231
	v_mov_b32_e32 v232, 0
	v_mov_b32_e32 v214, 0
	v_mov_b32_e32 v215, 0
	v_mov_b32_e32 v212, 0
	v_mov_b32_e32 v213, 0
	v_mov_b32_e32 v210, 0
	v_mov_b32_e32 v211, 0
	v_mov_b32_e32 v208, 0
	v_mov_b32_e32 v209, 0
	v_mov_b32_e32 v206, 0
	v_mov_b32_e32 v207, 0
	v_mov_b32_e32 v204, 0
	v_mov_b32_e32 v205, 0
	v_mov_b32_e32 v193, v217
	.p2alignl 6, 3212836864

.LBB0_1479:
	s_ashr_i32 s23, s22, 31
	v_cmp_lt_i64_e32 vcc, s[24:25], v[158:159]
	s_lshl_b64 s[24:25], s[22:23], 19
	s_add_u32 s24, s41, s24
	s_addc_u32 s25, s42, s25
	s_and_b64 s[26:27], vcc, exec
	s_cselect_b32 s23, s25, s35
	s_cselect_b32 s29, s24, s34
	s_ashr_i32 s21, s20, 31
	s_lshl_b64 s[26:27], s[20:21], 19
	s_add_u32 s26, s43, s26
	s_addc_u32 s27, s44, s27
	s_and_b64 s[36:37], vcc, exec
	s_cselect_b32 s21, s27, s31
	s_cselect_b32 s66, s26, s30
	s_add_u32 s67, s30, 0x100
	s_addc_u32 s68, s31, 0
	s_add_u32 s30, s34, 0x40080
	v_mov_b32_e32 v0, 0
	s_addc_u32 s31, s35, 0
	s_mov_b32 s69, -2
	s_waitcnt lgkmcnt(0)
	v_mov_b32_e32 v1, v0
	v_mov_b32_e32 v2, v0
	v_mov_b32_e32 v3, v0
	v_mov_b32_e32 v4, v0
	v_mov_b32_e32 v5, v0
	v_mov_b32_e32 v6, v0
	v_mov_b32_e32 v7, v0
	v_mov_b32_e32 v16, v0
	v_mov_b32_e32 v17, v0
	v_mov_b32_e32 v18, v0
	v_mov_b32_e32 v19, v0
	v_mov_b32_e32 v20, v0
	v_mov_b32_e32 v21, v0
	v_mov_b32_e32 v22, v0
	v_mov_b32_e32 v23, v0
	v_mov_b32_e32 v32, v0
	v_mov_b32_e32 v33, v0
	v_mov_b32_e32 v34, v0
	v_mov_b32_e32 v35, v0
	v_mov_b32_e32 v36, v0
	v_mov_b32_e32 v37, v0
	v_mov_b32_e32 v38, v0
	v_mov_b32_e32 v39, v0
	v_mov_b32_e32 v48, v0
	v_mov_b32_e32 v49, v0
	v_mov_b32_e32 v50, v0
	v_mov_b32_e32 v51, v0
	v_mov_b32_e32 v52, v0
	v_mov_b32_e32 v53, v0
	v_mov_b32_e32 v54, v0
	v_mov_b32_e32 v55, v0
	v_mov_b32_e32 v8, v0
	v_mov_b32_e32 v9, v0
	v_mov_b32_e32 v10, v0
	v_mov_b32_e32 v11, v0
	v_mov_b32_e32 v12, v0
	v_mov_b32_e32 v13, v0
	v_mov_b32_e32 v14, v0
	v_mov_b32_e32 v15, v0
	v_mov_b32_e32 v24, v0
	v_mov_b32_e32 v25, v0
	v_mov_b32_e32 v26, v0
	v_mov_b32_e32 v27, v0
	v_mov_b32_e32 v28, v0
	v_mov_b32_e32 v29, v0
	v_mov_b32_e32 v30, v0
	v_mov_b32_e32 v31, v0
	v_mov_b32_e32 v40, v0
	v_mov_b32_e32 v41, v0
	v_mov_b32_e32 v42, v0
	v_mov_b32_e32 v43, v0
	v_mov_b32_e32 v44, v0
	v_mov_b32_e32 v45, v0
	v_mov_b32_e32 v46, v0
	v_mov_b32_e32 v47, v0
	v_mov_b32_e32 v56, v0
	v_mov_b32_e32 v57, v0
	v_mov_b32_e32 v58, v0
	v_mov_b32_e32 v59, v0
	v_mov_b32_e32 v60, v0
	v_mov_b32_e32 v61, v0
	v_mov_b32_e32 v62, v0
	v_mov_b32_e32 v63, v0
	v_mov_b32_e32 v64, v0
	v_mov_b32_e32 v65, v0
	v_mov_b32_e32 v66, v0
	v_mov_b32_e32 v67, v0
	v_mov_b32_e32 v68, v0
	v_mov_b32_e32 v69, v0
	v_mov_b32_e32 v70, v0
	v_mov_b32_e32 v71, v0
	v_mov_b32_e32 v80, v0
	v_mov_b32_e32 v81, v0
	v_mov_b32_e32 v82, v0
	v_mov_b32_e32 v83, v0
	v_mov_b32_e32 v84, v0
	v_mov_b32_e32 v85, v0
	v_mov_b32_e32 v86, v0
	v_mov_b32_e32 v87, v0
	v_mov_b32_e32 v96, v0
	v_mov_b32_e32 v97, v0
	v_mov_b32_e32 v98, v0
	v_mov_b32_e32 v99, v0
	v_mov_b32_e32 v100, v0
	v_mov_b32_e32 v101, v0
	v_mov_b32_e32 v102, v0
	v_mov_b32_e32 v103, v0
	v_mov_b32_e32 v112, v0
	v_mov_b32_e32 v113, v0
	v_mov_b32_e32 v114, v0
	v_mov_b32_e32 v115, v0
	v_mov_b32_e32 v116, v0
	v_mov_b32_e32 v117, v0
	v_mov_b32_e32 v118, v0
	v_mov_b32_e32 v119, v0
	v_mov_b32_e32 v72, v0
	v_mov_b32_e32 v73, v0
	v_mov_b32_e32 v74, v0
	v_mov_b32_e32 v75, v0
	v_mov_b32_e32 v76, v0
	v_mov_b32_e32 v77, v0
	v_mov_b32_e32 v78, v0
	v_mov_b32_e32 v79, v0
	v_mov_b32_e32 v88, v0
	v_mov_b32_e32 v89, v0
	v_mov_b32_e32 v90, v0
	v_mov_b32_e32 v91, v0
	v_mov_b32_e32 v92, v0
	v_mov_b32_e32 v93, v0
	v_mov_b32_e32 v94, v0
	v_mov_b32_e32 v95, v0
	v_mov_b32_e32 v104, v0
	v_mov_b32_e32 v105, v0
	v_mov_b32_e32 v106, v0
	v_mov_b32_e32 v107, v0
	v_mov_b32_e32 v108, v0
	v_mov_b32_e32 v109, v0
	v_mov_b32_e32 v110, v0
	v_mov_b32_e32 v111, v0
	v_mov_b32_e32 v120, v0
	v_mov_b32_e32 v121, v0
	v_mov_b32_e32 v122, v0
	v_mov_b32_e32 v123, v0
	v_mov_b32_e32 v124, v0
	v_mov_b32_e32 v125, v0
	v_mov_b32_e32 v126, v0
	v_mov_b32_e32 v127, v0
	.p2alignl 6, 3212836864

.LBB0_1563:
	s_ashr_i32 s15, s14, 31
	v_cmp_lt_i64_e32 vcc, s[16:17], v[144:145]
	s_lshl_b64 s[16:17], s[14:15], 19
	s_add_u32 s16, s35, s16
	s_addc_u32 s17, s36, s17
	s_and_b64 s[18:19], vcc, exec
	s_cselect_b32 s15, s17, s25
	s_cselect_b32 s64, s16, s24
	s_ashr_i32 s13, s12, 31
	s_lshl_b64 s[18:19], s[12:13], 19
	s_add_u32 s18, s31, s18
	s_addc_u32 s19, s33, s19
	s_and_b64 s[26:27], vcc, exec
	s_cselect_b32 s13, s19, s23
	s_cselect_b32 s65, s18, s22
	s_add_u32 s66, s22, 0x100
	s_addc_u32 s67, s23, 0
	s_add_u32 s22, s24, 0x40080
	v_mov_b32_e32 v0, 0
	s_addc_u32 s23, s25, 0
	s_mov_b32 s68, -2
	v_mov_b32_e32 v1, v0
	v_mov_b32_e32 v2, v0
	v_mov_b32_e32 v3, v0
	v_mov_b32_e32 v4, v0
	v_mov_b32_e32 v5, v0
	v_mov_b32_e32 v6, v0
	v_mov_b32_e32 v7, v0
	v_mov_b32_e32 v16, v0
	v_mov_b32_e32 v17, v0
	v_mov_b32_e32 v18, v0
	v_mov_b32_e32 v19, v0
	v_mov_b32_e32 v20, v0
	v_mov_b32_e32 v21, v0
	v_mov_b32_e32 v22, v0
	v_mov_b32_e32 v23, v0
	v_mov_b32_e32 v32, v0
	v_mov_b32_e32 v33, v0
	v_mov_b32_e32 v34, v0
	v_mov_b32_e32 v35, v0
	v_mov_b32_e32 v36, v0
	v_mov_b32_e32 v37, v0
	v_mov_b32_e32 v38, v0
	v_mov_b32_e32 v39, v0
	v_mov_b32_e32 v48, v0
	v_mov_b32_e32 v49, v0
	v_mov_b32_e32 v50, v0
	v_mov_b32_e32 v51, v0
	v_mov_b32_e32 v52, v0
	v_mov_b32_e32 v53, v0
	v_mov_b32_e32 v54, v0
	v_mov_b32_e32 v55, v0
	v_mov_b32_e32 v8, v0
	v_mov_b32_e32 v9, v0
	v_mov_b32_e32 v10, v0
	v_mov_b32_e32 v11, v0
	v_mov_b32_e32 v12, v0
	v_mov_b32_e32 v13, v0
	v_mov_b32_e32 v14, v0
	v_mov_b32_e32 v15, v0
	v_mov_b32_e32 v24, v0
	v_mov_b32_e32 v25, v0
	v_mov_b32_e32 v26, v0
	v_mov_b32_e32 v27, v0
	v_mov_b32_e32 v28, v0
	v_mov_b32_e32 v29, v0
	v_mov_b32_e32 v30, v0
	v_mov_b32_e32 v31, v0
	v_mov_b32_e32 v40, v0
	v_mov_b32_e32 v41, v0
	v_mov_b32_e32 v42, v0
	v_mov_b32_e32 v43, v0
	v_mov_b32_e32 v44, v0
	v_mov_b32_e32 v45, v0
	v_mov_b32_e32 v46, v0
	v_mov_b32_e32 v47, v0
	v_mov_b32_e32 v56, v0
	v_mov_b32_e32 v57, v0
	v_mov_b32_e32 v58, v0
	v_mov_b32_e32 v59, v0
	v_mov_b32_e32 v60, v0
	v_mov_b32_e32 v61, v0
	v_mov_b32_e32 v62, v0
	v_mov_b32_e32 v63, v0
	v_mov_b32_e32 v64, v0
	v_mov_b32_e32 v65, v0
	v_mov_b32_e32 v66, v0
	v_mov_b32_e32 v67, v0
	v_mov_b32_e32 v68, v0
	v_mov_b32_e32 v69, v0
	v_mov_b32_e32 v70, v0
	v_mov_b32_e32 v71, v0
	v_mov_b32_e32 v80, v0
	v_mov_b32_e32 v81, v0
	v_mov_b32_e32 v82, v0
	v_mov_b32_e32 v83, v0
	v_mov_b32_e32 v84, v0
	v_mov_b32_e32 v85, v0
	v_mov_b32_e32 v86, v0
	v_mov_b32_e32 v87, v0
	v_mov_b32_e32 v96, v0
	v_mov_b32_e32 v97, v0
	v_mov_b32_e32 v98, v0
	v_mov_b32_e32 v99, v0
	v_mov_b32_e32 v100, v0
	v_mov_b32_e32 v101, v0
	v_mov_b32_e32 v102, v0
	v_mov_b32_e32 v103, v0
	v_mov_b32_e32 v112, v0
	v_mov_b32_e32 v113, v0
	v_mov_b32_e32 v114, v0
	v_mov_b32_e32 v115, v0
	v_mov_b32_e32 v116, v0
	v_mov_b32_e32 v117, v0
	v_mov_b32_e32 v118, v0
	v_mov_b32_e32 v119, v0
	v_mov_b32_e32 v72, v0
	v_mov_b32_e32 v73, v0
	v_mov_b32_e32 v74, v0
	v_mov_b32_e32 v75, v0
	v_mov_b32_e32 v76, v0
	v_mov_b32_e32 v77, v0
	v_mov_b32_e32 v78, v0
	v_mov_b32_e32 v79, v0
	v_mov_b32_e32 v88, v0
	v_mov_b32_e32 v89, v0
	v_mov_b32_e32 v90, v0
	v_mov_b32_e32 v91, v0
	v_mov_b32_e32 v92, v0
	v_mov_b32_e32 v93, v0
	v_mov_b32_e32 v94, v0
	v_mov_b32_e32 v95, v0
	v_mov_b32_e32 v104, v0
	v_mov_b32_e32 v105, v0
	v_mov_b32_e32 v106, v0
	v_mov_b32_e32 v107, v0
	v_mov_b32_e32 v108, v0
	v_mov_b32_e32 v109, v0
	v_mov_b32_e32 v110, v0
	v_mov_b32_e32 v111, v0
	v_mov_b32_e32 v120, v0
	v_mov_b32_e32 v121, v0
	v_mov_b32_e32 v122, v0
	v_mov_b32_e32 v123, v0
	v_mov_b32_e32 v124, v0
	v_mov_b32_e32 v125, v0
	v_mov_b32_e32 v126, v0
	v_mov_b32_e32 v127, v0
	.p2alignl 6, 3212836864

.LBB0_1641:
	s_add_u32 s25, s26, 0x100
	s_addc_u32 s64, s27, 0
	s_add_u32 s26, s28, 0xb0080
	v_mov_b32_e32 v0, 0
	s_addc_u32 s27, s29, 0
	s_mov_b32 s65, -2
	s_waitcnt lgkmcnt(0)
	v_mov_b32_e32 v1, v0
	v_mov_b32_e32 v2, v0
	v_mov_b32_e32 v3, v0
	v_mov_b32_e32 v4, v0
	v_mov_b32_e32 v5, v0
	v_mov_b32_e32 v6, v0
	v_mov_b32_e32 v7, v0
	v_mov_b32_e32 v16, v0
	v_mov_b32_e32 v17, v0
	v_mov_b32_e32 v18, v0
	v_mov_b32_e32 v19, v0
	v_mov_b32_e32 v20, v0
	v_mov_b32_e32 v21, v0
	v_mov_b32_e32 v22, v0
	v_mov_b32_e32 v23, v0
	v_mov_b32_e32 v32, v0
	v_mov_b32_e32 v33, v0
	v_mov_b32_e32 v34, v0
	v_mov_b32_e32 v35, v0
	v_mov_b32_e32 v36, v0
	v_mov_b32_e32 v37, v0
	v_mov_b32_e32 v38, v0
	v_mov_b32_e32 v39, v0
	v_mov_b32_e32 v48, v0
	v_mov_b32_e32 v49, v0
	v_mov_b32_e32 v50, v0
	v_mov_b32_e32 v51, v0
	v_mov_b32_e32 v52, v0
	v_mov_b32_e32 v53, v0
	v_mov_b32_e32 v54, v0
	v_mov_b32_e32 v55, v0
	v_mov_b32_e32 v8, v0
	v_mov_b32_e32 v9, v0
	v_mov_b32_e32 v10, v0
	v_mov_b32_e32 v11, v0
	v_mov_b32_e32 v12, v0
	v_mov_b32_e32 v13, v0
	v_mov_b32_e32 v14, v0
	v_mov_b32_e32 v15, v0
	v_mov_b32_e32 v24, v0
	v_mov_b32_e32 v25, v0
	v_mov_b32_e32 v26, v0
	v_mov_b32_e32 v27, v0
	v_mov_b32_e32 v28, v0
	v_mov_b32_e32 v29, v0
	v_mov_b32_e32 v30, v0
	v_mov_b32_e32 v31, v0
	v_mov_b32_e32 v40, v0
	v_mov_b32_e32 v41, v0
	v_mov_b32_e32 v42, v0
	v_mov_b32_e32 v43, v0
	v_mov_b32_e32 v44, v0
	v_mov_b32_e32 v45, v0
	v_mov_b32_e32 v46, v0
	v_mov_b32_e32 v47, v0
	v_mov_b32_e32 v56, v0
	v_mov_b32_e32 v57, v0
	v_mov_b32_e32 v58, v0
	v_mov_b32_e32 v59, v0
	v_mov_b32_e32 v60, v0
	v_mov_b32_e32 v61, v0
	v_mov_b32_e32 v62, v0
	v_mov_b32_e32 v63, v0
	v_mov_b32_e32 v64, v0
	v_mov_b32_e32 v65, v0
	v_mov_b32_e32 v66, v0
	v_mov_b32_e32 v67, v0
	v_mov_b32_e32 v68, v0
	v_mov_b32_e32 v69, v0
	v_mov_b32_e32 v70, v0
	v_mov_b32_e32 v71, v0
	v_mov_b32_e32 v80, v0
	v_mov_b32_e32 v81, v0
	v_mov_b32_e32 v82, v0
	v_mov_b32_e32 v83, v0
	v_mov_b32_e32 v84, v0
	v_mov_b32_e32 v85, v0
	v_mov_b32_e32 v86, v0
	v_mov_b32_e32 v87, v0
	v_mov_b32_e32 v96, v0
	v_mov_b32_e32 v97, v0
	v_mov_b32_e32 v98, v0
	v_mov_b32_e32 v99, v0
	v_mov_b32_e32 v100, v0
	v_mov_b32_e32 v101, v0
	v_mov_b32_e32 v102, v0
	v_mov_b32_e32 v103, v0
	v_mov_b32_e32 v112, v0
	v_mov_b32_e32 v113, v0
	v_mov_b32_e32 v114, v0
	v_mov_b32_e32 v115, v0
	v_mov_b32_e32 v116, v0
	v_mov_b32_e32 v117, v0
	v_mov_b32_e32 v118, v0
	v_mov_b32_e32 v119, v0
	v_mov_b32_e32 v72, v0
	v_mov_b32_e32 v73, v0
	v_mov_b32_e32 v74, v0
	v_mov_b32_e32 v75, v0
	v_mov_b32_e32 v76, v0
	v_mov_b32_e32 v77, v0
	v_mov_b32_e32 v78, v0
	v_mov_b32_e32 v79, v0
	v_mov_b32_e32 v88, v0
	v_mov_b32_e32 v89, v0
	v_mov_b32_e32 v90, v0
	v_mov_b32_e32 v91, v0
	v_mov_b32_e32 v92, v0
	v_mov_b32_e32 v93, v0
	v_mov_b32_e32 v94, v0
	v_mov_b32_e32 v95, v0
	v_mov_b32_e32 v104, v0
	v_mov_b32_e32 v105, v0
	v_mov_b32_e32 v106, v0
	v_mov_b32_e32 v107, v0
	v_mov_b32_e32 v108, v0
	v_mov_b32_e32 v109, v0
	v_mov_b32_e32 v110, v0
	v_mov_b32_e32 v111, v0
	v_mov_b32_e32 v120, v0
	v_mov_b32_e32 v121, v0
	v_mov_b32_e32 v122, v0
	v_mov_b32_e32 v123, v0
	v_mov_b32_e32 v124, v0
	v_mov_b32_e32 v125, v0
	v_mov_b32_e32 v126, v0
	v_mov_b32_e32 v127, v0
	.p2alignl 6, 3212836864

.LBB0_1726:
	s_ashr_i32 s21, s20, 31
	v_cmp_lt_i64_e32 vcc, s[22:23], v[164:165]
	s_lshl_b64 s[22:23], s[20:21], 19
	s_add_u32 s22, s41, s22
	s_addc_u32 s23, s42, s23
	s_and_b64 s[24:25], vcc, exec
	s_cselect_b32 s21, s23, s31
	s_cselect_b32 s27, s22, s30
	s_ashr_i32 s19, s18, 31
	s_lshl_b64 s[24:25], s[18:19], 19
	s_add_u32 s24, s38, s24
	s_addc_u32 s25, s39, s25
	s_and_b64 s[34:35], vcc, exec
	s_cselect_b32 s19, s25, s29
	s_cselect_b32 s83, s24, s28
	s_add_u32 s84, s28, 0x100
	s_addc_u32 s85, s29, 0
	s_add_u32 s28, s30, 0x40080
	v_mov_b32_e32 v0, 0
	s_addc_u32 s29, s31, 0
	s_mov_b32 s86, -2
	v_mov_b32_e32 v1, v0
	v_mov_b32_e32 v2, v0
	v_mov_b32_e32 v3, v0
	v_mov_b32_e32 v4, v0
	v_mov_b32_e32 v5, v0
	v_mov_b32_e32 v6, v0
	v_mov_b32_e32 v7, v0
	v_mov_b32_e32 v16, v0
	v_mov_b32_e32 v17, v0
	v_mov_b32_e32 v18, v0
	v_mov_b32_e32 v19, v0
	v_mov_b32_e32 v20, v0
	v_mov_b32_e32 v21, v0
	v_mov_b32_e32 v22, v0
	v_mov_b32_e32 v23, v0
	v_mov_b32_e32 v32, v0
	v_mov_b32_e32 v33, v0
	v_mov_b32_e32 v34, v0
	v_mov_b32_e32 v35, v0
	v_mov_b32_e32 v36, v0
	v_mov_b32_e32 v37, v0
	v_mov_b32_e32 v38, v0
	v_mov_b32_e32 v39, v0
	v_mov_b32_e32 v48, v0
	v_mov_b32_e32 v49, v0
	v_mov_b32_e32 v50, v0
	v_mov_b32_e32 v51, v0
	v_mov_b32_e32 v52, v0
	v_mov_b32_e32 v53, v0
	v_mov_b32_e32 v54, v0
	v_mov_b32_e32 v55, v0
	v_mov_b32_e32 v8, v0
	v_mov_b32_e32 v9, v0
	v_mov_b32_e32 v10, v0
	v_mov_b32_e32 v11, v0
	v_mov_b32_e32 v12, v0
	v_mov_b32_e32 v13, v0
	v_mov_b32_e32 v14, v0
	v_mov_b32_e32 v15, v0
	v_mov_b32_e32 v24, v0
	v_mov_b32_e32 v25, v0
	v_mov_b32_e32 v26, v0
	v_mov_b32_e32 v27, v0
	v_mov_b32_e32 v28, v0
	v_mov_b32_e32 v29, v0
	v_mov_b32_e32 v30, v0
	v_mov_b32_e32 v31, v0
	v_mov_b32_e32 v40, v0
	v_mov_b32_e32 v41, v0
	v_mov_b32_e32 v42, v0
	v_mov_b32_e32 v43, v0
	v_mov_b32_e32 v44, v0
	v_mov_b32_e32 v45, v0
	v_mov_b32_e32 v46, v0
	v_mov_b32_e32 v47, v0
	v_mov_b32_e32 v56, v0
	v_mov_b32_e32 v57, v0
	v_mov_b32_e32 v58, v0
	v_mov_b32_e32 v59, v0
	v_mov_b32_e32 v60, v0
	v_mov_b32_e32 v61, v0
	v_mov_b32_e32 v62, v0
	v_mov_b32_e32 v63, v0
	v_mov_b32_e32 v64, v0
	v_mov_b32_e32 v65, v0
	v_mov_b32_e32 v66, v0
	v_mov_b32_e32 v67, v0
	v_mov_b32_e32 v68, v0
	v_mov_b32_e32 v69, v0
	v_mov_b32_e32 v70, v0
	v_mov_b32_e32 v71, v0
	v_mov_b32_e32 v80, v0
	v_mov_b32_e32 v81, v0
	v_mov_b32_e32 v82, v0
	v_mov_b32_e32 v83, v0
	v_mov_b32_e32 v84, v0
	v_mov_b32_e32 v85, v0
	v_mov_b32_e32 v86, v0
	v_mov_b32_e32 v87, v0
	v_mov_b32_e32 v96, v0
	v_mov_b32_e32 v97, v0
	v_mov_b32_e32 v98, v0
	v_mov_b32_e32 v99, v0
	v_mov_b32_e32 v100, v0
	v_mov_b32_e32 v101, v0
	v_mov_b32_e32 v102, v0
	v_mov_b32_e32 v103, v0
	v_mov_b32_e32 v112, v0
	v_mov_b32_e32 v113, v0
	v_mov_b32_e32 v114, v0
	v_mov_b32_e32 v115, v0
	v_mov_b32_e32 v116, v0
	v_mov_b32_e32 v117, v0
	v_mov_b32_e32 v118, v0
	v_mov_b32_e32 v119, v0
	v_mov_b32_e32 v72, v0
	v_mov_b32_e32 v73, v0
	v_mov_b32_e32 v74, v0
	v_mov_b32_e32 v75, v0
	v_mov_b32_e32 v76, v0
	v_mov_b32_e32 v77, v0
	v_mov_b32_e32 v78, v0
	v_mov_b32_e32 v79, v0
	v_mov_b32_e32 v88, v0
	v_mov_b32_e32 v89, v0
	v_mov_b32_e32 v90, v0
	v_mov_b32_e32 v91, v0
	v_mov_b32_e32 v92, v0
	v_mov_b32_e32 v93, v0
	v_mov_b32_e32 v94, v0
	v_mov_b32_e32 v95, v0
	v_mov_b32_e32 v104, v0
	v_mov_b32_e32 v105, v0
	v_mov_b32_e32 v106, v0
	v_mov_b32_e32 v107, v0
	v_mov_b32_e32 v108, v0
	v_mov_b32_e32 v109, v0
	v_mov_b32_e32 v110, v0
	v_mov_b32_e32 v111, v0
	v_mov_b32_e32 v120, v0
	v_mov_b32_e32 v121, v0
	v_mov_b32_e32 v122, v0
	v_mov_b32_e32 v123, v0
	v_mov_b32_e32 v124, v0
	v_mov_b32_e32 v125, v0
	v_mov_b32_e32 v126, v0
	v_mov_b32_e32 v127, v0
	.p2alignl 6, 3212836864

.LBB0_1811:
	s_add_u32 s27, s28, 0x100
	s_addc_u32 s66, s29, 0
	s_add_u32 s28, s30, 0xb0080
	v_mov_b32_e32 v0, 0
	s_addc_u32 s29, s31, 0
	s_mov_b32 s67, -2
	s_waitcnt lgkmcnt(0)
	v_mov_b32_e32 v1, v0
	v_mov_b32_e32 v2, v0
	v_mov_b32_e32 v3, v0
	v_mov_b32_e32 v4, v0
	v_mov_b32_e32 v5, v0
	v_mov_b32_e32 v6, v0
	v_mov_b32_e32 v7, v0
	v_mov_b32_e32 v16, v0
	v_mov_b32_e32 v17, v0
	v_mov_b32_e32 v18, v0
	v_mov_b32_e32 v19, v0
	v_mov_b32_e32 v20, v0
	v_mov_b32_e32 v21, v0
	v_mov_b32_e32 v22, v0
	v_mov_b32_e32 v23, v0
	v_mov_b32_e32 v32, v0
	v_mov_b32_e32 v33, v0
	v_mov_b32_e32 v34, v0
	v_mov_b32_e32 v35, v0
	v_mov_b32_e32 v36, v0
	v_mov_b32_e32 v37, v0
	v_mov_b32_e32 v38, v0
	v_mov_b32_e32 v39, v0
	v_mov_b32_e32 v48, v0
	v_mov_b32_e32 v49, v0
	v_mov_b32_e32 v50, v0
	v_mov_b32_e32 v51, v0
	v_mov_b32_e32 v52, v0
	v_mov_b32_e32 v53, v0
	v_mov_b32_e32 v54, v0
	v_mov_b32_e32 v55, v0
	v_mov_b32_e32 v8, v0
	v_mov_b32_e32 v9, v0
	v_mov_b32_e32 v10, v0
	v_mov_b32_e32 v11, v0
	v_mov_b32_e32 v12, v0
	v_mov_b32_e32 v13, v0
	v_mov_b32_e32 v14, v0
	v_mov_b32_e32 v15, v0
	v_mov_b32_e32 v24, v0
	v_mov_b32_e32 v25, v0
	v_mov_b32_e32 v26, v0
	v_mov_b32_e32 v27, v0
	v_mov_b32_e32 v28, v0
	v_mov_b32_e32 v29, v0
	v_mov_b32_e32 v30, v0
	v_mov_b32_e32 v31, v0
	v_mov_b32_e32 v40, v0
	v_mov_b32_e32 v41, v0
	v_mov_b32_e32 v42, v0
	v_mov_b32_e32 v43, v0
	v_mov_b32_e32 v44, v0
	v_mov_b32_e32 v45, v0
	v_mov_b32_e32 v46, v0
	v_mov_b32_e32 v47, v0
	v_mov_b32_e32 v56, v0
	v_mov_b32_e32 v57, v0
	v_mov_b32_e32 v58, v0
	v_mov_b32_e32 v59, v0
	v_mov_b32_e32 v60, v0
	v_mov_b32_e32 v61, v0
	v_mov_b32_e32 v62, v0
	v_mov_b32_e32 v63, v0
	v_mov_b32_e32 v64, v0
	v_mov_b32_e32 v65, v0
	v_mov_b32_e32 v66, v0
	v_mov_b32_e32 v67, v0
	v_mov_b32_e32 v68, v0
	v_mov_b32_e32 v69, v0
	v_mov_b32_e32 v70, v0
	v_mov_b32_e32 v71, v0
	v_mov_b32_e32 v80, v0
	v_mov_b32_e32 v81, v0
	v_mov_b32_e32 v82, v0
	v_mov_b32_e32 v83, v0
	v_mov_b32_e32 v84, v0
	v_mov_b32_e32 v85, v0
	v_mov_b32_e32 v86, v0
	v_mov_b32_e32 v87, v0
	v_mov_b32_e32 v96, v0
	v_mov_b32_e32 v97, v0
	v_mov_b32_e32 v98, v0
	v_mov_b32_e32 v99, v0
	v_mov_b32_e32 v100, v0
	v_mov_b32_e32 v101, v0
	v_mov_b32_e32 v102, v0
	v_mov_b32_e32 v103, v0
	v_mov_b32_e32 v112, v0
	v_mov_b32_e32 v113, v0
	v_mov_b32_e32 v114, v0
	v_mov_b32_e32 v115, v0
	v_mov_b32_e32 v116, v0
	v_mov_b32_e32 v117, v0
	v_mov_b32_e32 v118, v0
	v_mov_b32_e32 v119, v0
	v_mov_b32_e32 v72, v0
	v_mov_b32_e32 v73, v0
	v_mov_b32_e32 v74, v0
	v_mov_b32_e32 v75, v0
	v_mov_b32_e32 v76, v0
	v_mov_b32_e32 v77, v0
	v_mov_b32_e32 v78, v0
	v_mov_b32_e32 v79, v0
	v_mov_b32_e32 v88, v0
	v_mov_b32_e32 v89, v0
	v_mov_b32_e32 v90, v0
	v_mov_b32_e32 v91, v0
	v_mov_b32_e32 v92, v0
	v_mov_b32_e32 v93, v0
	v_mov_b32_e32 v94, v0
	v_mov_b32_e32 v95, v0
	v_mov_b32_e32 v104, v0
	v_mov_b32_e32 v105, v0
	v_mov_b32_e32 v106, v0
	v_mov_b32_e32 v107, v0
	v_mov_b32_e32 v108, v0
	v_mov_b32_e32 v109, v0
	v_mov_b32_e32 v110, v0
	v_mov_b32_e32 v111, v0
	v_mov_b32_e32 v120, v0
	v_mov_b32_e32 v121, v0
	v_mov_b32_e32 v122, v0
	v_mov_b32_e32 v123, v0
	v_mov_b32_e32 v124, v0
	v_mov_b32_e32 v125, v0
	v_mov_b32_e32 v126, v0
	v_mov_b32_e32 v127, v0
	.p2alignl 6, 3212836864

.LBB0_1914:
	s_ashr_i32 s73, s72, 31
	v_cmp_lt_i64_e32 vcc, s[14:15], v[144:145]
	s_lshl_b64 s[14:15], s[72:73], 19
	s_add_u32 s50, s33, s14
	s_addc_u32 s51, s34, s15
	s_and_b64 s[16:17], vcc, exec
	s_cselect_b32 s13, s51, s23
	s_cselect_b32 s63, s50, s22
	s_ashr_i32 s11, s10, 31
	s_lshl_b64 s[16:17], s[10:11], 19
	s_add_u32 s70, s29, s16
	s_addc_u32 s71, s30, s17
	s_and_b64 s[24:25], vcc, exec
	s_cselect_b32 s11, s71, s21
	s_cselect_b32 s64, s70, s20
	s_add_u32 s65, s20, 0x100
	s_addc_u32 s66, s21, 0
	s_add_u32 s20, s22, 0x40080
	v_mov_b32_e32 v0, 0
	s_addc_u32 s21, s23, 0
	s_mov_b32 s67, -2
	v_mov_b32_e32 v1, v0
	v_mov_b32_e32 v2, v0
	v_mov_b32_e32 v3, v0
	v_mov_b32_e32 v4, v0
	v_mov_b32_e32 v5, v0
	v_mov_b32_e32 v6, v0
	v_mov_b32_e32 v7, v0
	v_mov_b32_e32 v12, v0
	v_mov_b32_e32 v13, v0
	v_mov_b32_e32 v14, v0
	v_mov_b32_e32 v15, v0
	v_mov_b32_e32 v20, v0
	v_mov_b32_e32 v21, v0
	v_mov_b32_e32 v22, v0
	v_mov_b32_e32 v23, v0
	v_mov_b32_e32 v28, v0
	v_mov_b32_e32 v29, v0
	v_mov_b32_e32 v30, v0
	v_mov_b32_e32 v31, v0
	v_mov_b32_e32 v36, v0
	v_mov_b32_e32 v37, v0
	v_mov_b32_e32 v38, v0
	v_mov_b32_e32 v39, v0
	v_mov_b32_e32 v44, v0
	v_mov_b32_e32 v45, v0
	v_mov_b32_e32 v46, v0
	v_mov_b32_e32 v47, v0
	v_mov_b32_e32 v52, v0
	v_mov_b32_e32 v53, v0
	v_mov_b32_e32 v54, v0
	v_mov_b32_e32 v55, v0
	v_mov_b32_e32 v8, v0
	v_mov_b32_e32 v9, v0
	v_mov_b32_e32 v10, v0
	v_mov_b32_e32 v11, v0
	v_mov_b32_e32 v16, v0
	v_mov_b32_e32 v17, v0
	v_mov_b32_e32 v18, v0
	v_mov_b32_e32 v19, v0
	v_mov_b32_e32 v24, v0
	v_mov_b32_e32 v25, v0
	v_mov_b32_e32 v26, v0
	v_mov_b32_e32 v27, v0
	v_mov_b32_e32 v32, v0
	v_mov_b32_e32 v33, v0
	v_mov_b32_e32 v34, v0
	v_mov_b32_e32 v35, v0
	v_mov_b32_e32 v40, v0
	v_mov_b32_e32 v41, v0
	v_mov_b32_e32 v42, v0
	v_mov_b32_e32 v43, v0
	v_mov_b32_e32 v48, v0
	v_mov_b32_e32 v49, v0
	v_mov_b32_e32 v50, v0
	v_mov_b32_e32 v51, v0
	v_mov_b32_e32 v56, v0
	v_mov_b32_e32 v57, v0
	v_mov_b32_e32 v58, v0
	v_mov_b32_e32 v59, v0
	v_mov_b32_e32 v60, v0
	v_mov_b32_e32 v61, v0
	v_mov_b32_e32 v62, v0
	v_mov_b32_e32 v63, v0
	v_mov_b32_e32 v64, v0
	v_mov_b32_e32 v65, v0
	v_mov_b32_e32 v66, v0
	v_mov_b32_e32 v67, v0
	v_mov_b32_e32 v68, v0
	v_mov_b32_e32 v69, v0
	v_mov_b32_e32 v70, v0
	v_mov_b32_e32 v71, v0
	v_mov_b32_e32 v76, v0
	v_mov_b32_e32 v77, v0
	v_mov_b32_e32 v78, v0
	v_mov_b32_e32 v79, v0
	v_mov_b32_e32 v84, v0
	v_mov_b32_e32 v85, v0
	v_mov_b32_e32 v86, v0
	v_mov_b32_e32 v87, v0
	v_mov_b32_e32 v92, v0
	v_mov_b32_e32 v93, v0
	v_mov_b32_e32 v94, v0
	v_mov_b32_e32 v95, v0
	v_mov_b32_e32 v100, v0
	v_mov_b32_e32 v101, v0
	v_mov_b32_e32 v102, v0
	v_mov_b32_e32 v103, v0
	v_mov_b32_e32 v108, v0
	v_mov_b32_e32 v109, v0
	v_mov_b32_e32 v110, v0
	v_mov_b32_e32 v111, v0
	v_mov_b32_e32 v116, v0
	v_mov_b32_e32 v117, v0
	v_mov_b32_e32 v118, v0
	v_mov_b32_e32 v119, v0
	v_mov_b32_e32 v72, v0
	v_mov_b32_e32 v73, v0
	v_mov_b32_e32 v74, v0
	v_mov_b32_e32 v75, v0
	v_mov_b32_e32 v80, v0
	v_mov_b32_e32 v81, v0
	v_mov_b32_e32 v82, v0
	v_mov_b32_e32 v83, v0
	v_mov_b32_e32 v88, v0
	v_mov_b32_e32 v89, v0
	v_mov_b32_e32 v90, v0
	v_mov_b32_e32 v91, v0
	v_mov_b32_e32 v96, v0
	v_mov_b32_e32 v97, v0
	v_mov_b32_e32 v98, v0
	v_mov_b32_e32 v99, v0
	v_mov_b32_e32 v104, v0
	v_mov_b32_e32 v105, v0
	v_mov_b32_e32 v106, v0
	v_mov_b32_e32 v107, v0
	v_mov_b32_e32 v112, v0
	v_mov_b32_e32 v113, v0
	v_mov_b32_e32 v114, v0
	v_mov_b32_e32 v115, v0
	v_mov_b32_e32 v120, v0
	v_mov_b32_e32 v121, v0
	v_mov_b32_e32 v122, v0
	v_mov_b32_e32 v123, v0
	v_mov_b32_e32 v124, v0
	v_mov_b32_e32 v125, v0
	v_mov_b32_e32 v126, v0
	v_mov_b32_e32 v127, v0
	.p2alignl 6, 3212836864

.LBB0_1986:
	v_add_u32_e32 v0, 8, v72
	v_cmp_lt_u32_e32 vcc, 39, v72
	v_add_u32_e32 v71, 0x80, v71
	s_or_b64 s[54:55], vcc, s[54:55]
	v_mov_b32_e32 v72, v0
	s_andn2_b64 exec, exec, s[54:55]
	s_cbranch_execz .LBB0_1984
	.p2alignl 6, 3212836864

.LBB0_2163:
	s_ashr_i32 s23, s22, 31
	v_cmp_lt_i64_e32 vcc, s[24:25], v[158:159]
	s_lshl_b64 s[24:25], s[22:23], 19
	s_add_u32 s24, s41, s24
	s_addc_u32 s25, s42, s25
	s_and_b64 s[26:27], vcc, exec
	s_cselect_b32 s23, s25, s35
	s_cselect_b32 s29, s24, s34
	s_ashr_i32 s21, s20, 31
	s_lshl_b64 s[26:27], s[20:21], 19
	s_add_u32 s26, s43, s26
	s_addc_u32 s27, s44, s27
	s_and_b64 s[36:37], vcc, exec
	s_cselect_b32 s21, s27, s31
	s_cselect_b32 s64, s26, s30
	s_add_u32 s65, s30, 0x100
	s_addc_u32 s66, s31, 0
	s_add_u32 s30, s34, 0x40080
	v_mov_b32_e32 v0, 0
	s_addc_u32 s31, s35, 0
	s_mov_b32 s67, -2
	s_waitcnt lgkmcnt(0)
	v_mov_b32_e32 v1, v0
	v_mov_b32_e32 v2, v0
	v_mov_b32_e32 v3, v0
	v_mov_b32_e32 v4, v0
	v_mov_b32_e32 v5, v0
	v_mov_b32_e32 v6, v0
	v_mov_b32_e32 v7, v0
	v_mov_b32_e32 v16, v0
	v_mov_b32_e32 v17, v0
	v_mov_b32_e32 v18, v0
	v_mov_b32_e32 v19, v0
	v_mov_b32_e32 v20, v0
	v_mov_b32_e32 v21, v0
	v_mov_b32_e32 v22, v0
	v_mov_b32_e32 v23, v0
	v_mov_b32_e32 v32, v0
	v_mov_b32_e32 v33, v0
	v_mov_b32_e32 v34, v0
	v_mov_b32_e32 v35, v0
	v_mov_b32_e32 v36, v0
	v_mov_b32_e32 v37, v0
	v_mov_b32_e32 v38, v0
	v_mov_b32_e32 v39, v0
	v_mov_b32_e32 v48, v0
	v_mov_b32_e32 v49, v0
	v_mov_b32_e32 v50, v0
	v_mov_b32_e32 v51, v0
	v_mov_b32_e32 v52, v0
	v_mov_b32_e32 v53, v0
	v_mov_b32_e32 v54, v0
	v_mov_b32_e32 v55, v0
	v_mov_b32_e32 v8, v0
	v_mov_b32_e32 v9, v0
	v_mov_b32_e32 v10, v0
	v_mov_b32_e32 v11, v0
	v_mov_b32_e32 v12, v0
	v_mov_b32_e32 v13, v0
	v_mov_b32_e32 v14, v0
	v_mov_b32_e32 v15, v0
	v_mov_b32_e32 v24, v0
	v_mov_b32_e32 v25, v0
	v_mov_b32_e32 v26, v0
	v_mov_b32_e32 v27, v0
	v_mov_b32_e32 v28, v0
	v_mov_b32_e32 v29, v0
	v_mov_b32_e32 v30, v0
	v_mov_b32_e32 v31, v0
	v_mov_b32_e32 v40, v0
	v_mov_b32_e32 v41, v0
	v_mov_b32_e32 v42, v0
	v_mov_b32_e32 v43, v0
	v_mov_b32_e32 v44, v0
	v_mov_b32_e32 v45, v0
	v_mov_b32_e32 v46, v0
	v_mov_b32_e32 v47, v0
	v_mov_b32_e32 v56, v0
	v_mov_b32_e32 v57, v0
	v_mov_b32_e32 v58, v0
	v_mov_b32_e32 v59, v0
	v_mov_b32_e32 v60, v0
	v_mov_b32_e32 v61, v0
	v_mov_b32_e32 v62, v0
	v_mov_b32_e32 v63, v0
	v_mov_b32_e32 v64, v0
	v_mov_b32_e32 v65, v0
	v_mov_b32_e32 v66, v0
	v_mov_b32_e32 v67, v0
	v_mov_b32_e32 v68, v0
	v_mov_b32_e32 v69, v0
	v_mov_b32_e32 v70, v0
	v_mov_b32_e32 v71, v0
	v_mov_b32_e32 v80, v0
	v_mov_b32_e32 v81, v0
	v_mov_b32_e32 v82, v0
	v_mov_b32_e32 v83, v0
	v_mov_b32_e32 v84, v0
	v_mov_b32_e32 v85, v0
	v_mov_b32_e32 v86, v0
	v_mov_b32_e32 v87, v0
	v_mov_b32_e32 v96, v0
	v_mov_b32_e32 v97, v0
	v_mov_b32_e32 v98, v0
	v_mov_b32_e32 v99, v0
	v_mov_b32_e32 v100, v0
	v_mov_b32_e32 v101, v0
	v_mov_b32_e32 v102, v0
	v_mov_b32_e32 v103, v0
	v_mov_b32_e32 v112, v0
	v_mov_b32_e32 v113, v0
	v_mov_b32_e32 v114, v0
	v_mov_b32_e32 v115, v0
	v_mov_b32_e32 v116, v0
	v_mov_b32_e32 v117, v0
	v_mov_b32_e32 v118, v0
	v_mov_b32_e32 v119, v0
	v_mov_b32_e32 v72, v0
	v_mov_b32_e32 v73, v0
	v_mov_b32_e32 v74, v0
	v_mov_b32_e32 v75, v0
	v_mov_b32_e32 v76, v0
	v_mov_b32_e32 v77, v0
	v_mov_b32_e32 v78, v0
	v_mov_b32_e32 v79, v0
	v_mov_b32_e32 v88, v0
	v_mov_b32_e32 v89, v0
	v_mov_b32_e32 v90, v0
	v_mov_b32_e32 v91, v0
	v_mov_b32_e32 v92, v0
	v_mov_b32_e32 v93, v0
	v_mov_b32_e32 v94, v0
	v_mov_b32_e32 v95, v0
	v_mov_b32_e32 v104, v0
	v_mov_b32_e32 v105, v0
	v_mov_b32_e32 v106, v0
	v_mov_b32_e32 v107, v0
	v_mov_b32_e32 v108, v0
	v_mov_b32_e32 v109, v0
	v_mov_b32_e32 v110, v0
	v_mov_b32_e32 v111, v0
	v_mov_b32_e32 v120, v0
	v_mov_b32_e32 v121, v0
	v_mov_b32_e32 v122, v0
	v_mov_b32_e32 v123, v0
	v_mov_b32_e32 v124, v0
	v_mov_b32_e32 v125, v0
	v_mov_b32_e32 v126, v0
	v_mov_b32_e32 v127, v0
	.p2alignl 6, 3212836864

.LBB0_2247:
	s_ashr_i32 s15, s14, 31
	v_cmp_lt_i64_e32 vcc, s[16:17], v[144:145]
	s_lshl_b64 s[16:17], s[14:15], 19
	s_add_u32 s16, s35, s16
	s_addc_u32 s17, s36, s17
	s_and_b64 s[18:19], vcc, exec
	s_cselect_b32 s15, s17, s25
	s_cselect_b32 s62, s16, s24
	s_ashr_i32 s13, s12, 31
	s_lshl_b64 s[18:19], s[12:13], 19
	s_add_u32 s18, s31, s18
	s_addc_u32 s19, s33, s19
	s_and_b64 s[26:27], vcc, exec
	s_cselect_b32 s13, s19, s23
	s_cselect_b32 s63, s18, s22
	s_add_u32 s64, s22, 0x100
	s_addc_u32 s65, s23, 0
	s_add_u32 s22, s24, 0x40080
	v_mov_b32_e32 v0, 0
	s_addc_u32 s23, s25, 0
	s_mov_b32 s66, -2
	v_mov_b32_e32 v1, v0
	v_mov_b32_e32 v2, v0
	v_mov_b32_e32 v3, v0
	v_mov_b32_e32 v4, v0
	v_mov_b32_e32 v5, v0
	v_mov_b32_e32 v6, v0
	v_mov_b32_e32 v7, v0
	v_mov_b32_e32 v16, v0
	v_mov_b32_e32 v17, v0
	v_mov_b32_e32 v18, v0
	v_mov_b32_e32 v19, v0
	v_mov_b32_e32 v20, v0
	v_mov_b32_e32 v21, v0
	v_mov_b32_e32 v22, v0
	v_mov_b32_e32 v23, v0
	v_mov_b32_e32 v32, v0
	v_mov_b32_e32 v33, v0
	v_mov_b32_e32 v34, v0
	v_mov_b32_e32 v35, v0
	v_mov_b32_e32 v36, v0
	v_mov_b32_e32 v37, v0
	v_mov_b32_e32 v38, v0
	v_mov_b32_e32 v39, v0
	v_mov_b32_e32 v48, v0
	v_mov_b32_e32 v49, v0
	v_mov_b32_e32 v50, v0
	v_mov_b32_e32 v51, v0
	v_mov_b32_e32 v52, v0
	v_mov_b32_e32 v53, v0
	v_mov_b32_e32 v54, v0
	v_mov_b32_e32 v55, v0
	v_mov_b32_e32 v8, v0
	v_mov_b32_e32 v9, v0
	v_mov_b32_e32 v10, v0
	v_mov_b32_e32 v11, v0
	v_mov_b32_e32 v12, v0
	v_mov_b32_e32 v13, v0
	v_mov_b32_e32 v14, v0
	v_mov_b32_e32 v15, v0
	v_mov_b32_e32 v24, v0
	v_mov_b32_e32 v25, v0
	v_mov_b32_e32 v26, v0
	v_mov_b32_e32 v27, v0
	v_mov_b32_e32 v28, v0
	v_mov_b32_e32 v29, v0
	v_mov_b32_e32 v30, v0
	v_mov_b32_e32 v31, v0
	v_mov_b32_e32 v40, v0
	v_mov_b32_e32 v41, v0
	v_mov_b32_e32 v42, v0
	v_mov_b32_e32 v43, v0
	v_mov_b32_e32 v44, v0
	v_mov_b32_e32 v45, v0
	v_mov_b32_e32 v46, v0
	v_mov_b32_e32 v47, v0
	v_mov_b32_e32 v56, v0
	v_mov_b32_e32 v57, v0
	v_mov_b32_e32 v58, v0
	v_mov_b32_e32 v59, v0
	v_mov_b32_e32 v60, v0
	v_mov_b32_e32 v61, v0
	v_mov_b32_e32 v62, v0
	v_mov_b32_e32 v63, v0
	v_mov_b32_e32 v64, v0
	v_mov_b32_e32 v65, v0
	v_mov_b32_e32 v66, v0
	v_mov_b32_e32 v67, v0
	v_mov_b32_e32 v68, v0
	v_mov_b32_e32 v69, v0
	v_mov_b32_e32 v70, v0
	v_mov_b32_e32 v71, v0
	v_mov_b32_e32 v80, v0
	v_mov_b32_e32 v81, v0
	v_mov_b32_e32 v82, v0
	v_mov_b32_e32 v83, v0
	v_mov_b32_e32 v84, v0
	v_mov_b32_e32 v85, v0
	v_mov_b32_e32 v86, v0
	v_mov_b32_e32 v87, v0
	v_mov_b32_e32 v96, v0
	v_mov_b32_e32 v97, v0
	v_mov_b32_e32 v98, v0
	v_mov_b32_e32 v99, v0
	v_mov_b32_e32 v100, v0
	v_mov_b32_e32 v101, v0
	v_mov_b32_e32 v102, v0
	v_mov_b32_e32 v103, v0
	v_mov_b32_e32 v112, v0
	v_mov_b32_e32 v113, v0
	v_mov_b32_e32 v114, v0
	v_mov_b32_e32 v115, v0
	v_mov_b32_e32 v116, v0
	v_mov_b32_e32 v117, v0
	v_mov_b32_e32 v118, v0
	v_mov_b32_e32 v119, v0
	v_mov_b32_e32 v72, v0
	v_mov_b32_e32 v73, v0
	v_mov_b32_e32 v74, v0
	v_mov_b32_e32 v75, v0
	v_mov_b32_e32 v76, v0
	v_mov_b32_e32 v77, v0
	v_mov_b32_e32 v78, v0
	v_mov_b32_e32 v79, v0
	v_mov_b32_e32 v88, v0
	v_mov_b32_e32 v89, v0
	v_mov_b32_e32 v90, v0
	v_mov_b32_e32 v91, v0
	v_mov_b32_e32 v92, v0
	v_mov_b32_e32 v93, v0
	v_mov_b32_e32 v94, v0
	v_mov_b32_e32 v95, v0
	v_mov_b32_e32 v104, v0
	v_mov_b32_e32 v105, v0
	v_mov_b32_e32 v106, v0
	v_mov_b32_e32 v107, v0
	v_mov_b32_e32 v108, v0
	v_mov_b32_e32 v109, v0
	v_mov_b32_e32 v110, v0
	v_mov_b32_e32 v111, v0
	v_mov_b32_e32 v120, v0
	v_mov_b32_e32 v121, v0
	v_mov_b32_e32 v122, v0
	v_mov_b32_e32 v123, v0
	v_mov_b32_e32 v124, v0
	v_mov_b32_e32 v125, v0
	v_mov_b32_e32 v126, v0
	v_mov_b32_e32 v127, v0
	.p2alignl 6, 3212836864

.LBB0_2322:
	s_add_u32 s17, s18, 0x100
	s_addc_u32 s54, s19, 0
	s_add_u32 s18, s20, 0xb0080
	v_mov_b32_e32 v0, 0
	s_addc_u32 s19, s21, 0
	s_mov_b32 s55, -2
	v_mov_b32_e32 v1, v0
	v_mov_b32_e32 v2, v0
	v_mov_b32_e32 v3, v0
	v_mov_b32_e32 v4, v0
	v_mov_b32_e32 v5, v0
	v_mov_b32_e32 v6, v0
	v_mov_b32_e32 v7, v0
	v_mov_b32_e32 v8, v0
	v_mov_b32_e32 v9, v0
	v_mov_b32_e32 v10, v0
	v_mov_b32_e32 v11, v0
	v_mov_b32_e32 v12, v0
	v_mov_b32_e32 v13, v0
	v_mov_b32_e32 v14, v0
	v_mov_b32_e32 v15, v0
	v_mov_b32_e32 v32, v0
	v_mov_b32_e32 v33, v0
	v_mov_b32_e32 v34, v0
	v_mov_b32_e32 v35, v0
	v_mov_b32_e32 v36, v0
	v_mov_b32_e32 v37, v0
	v_mov_b32_e32 v38, v0
	v_mov_b32_e32 v39, v0
	v_mov_b32_e32 v40, v0
	v_mov_b32_e32 v41, v0
	v_mov_b32_e32 v42, v0
	v_mov_b32_e32 v43, v0
	v_mov_b32_e32 v44, v0
	v_mov_b32_e32 v45, v0
	v_mov_b32_e32 v46, v0
	v_mov_b32_e32 v47, v0
	v_mov_b32_e32 v16, v0
	v_mov_b32_e32 v17, v0
	v_mov_b32_e32 v18, v0
	v_mov_b32_e32 v19, v0
	v_mov_b32_e32 v20, v0
	v_mov_b32_e32 v21, v0
	v_mov_b32_e32 v22, v0
	v_mov_b32_e32 v23, v0
	v_mov_b32_e32 v24, v0
	v_mov_b32_e32 v25, v0
	v_mov_b32_e32 v26, v0
	v_mov_b32_e32 v27, v0
	v_mov_b32_e32 v28, v0
	v_mov_b32_e32 v29, v0
	v_mov_b32_e32 v30, v0
	v_mov_b32_e32 v31, v0
	v_mov_b32_e32 v48, v0
	v_mov_b32_e32 v49, v0
	v_mov_b32_e32 v50, v0
	v_mov_b32_e32 v51, v0
	v_mov_b32_e32 v52, v0
	v_mov_b32_e32 v53, v0
	v_mov_b32_e32 v54, v0
	v_mov_b32_e32 v55, v0
	v_mov_b32_e32 v56, v0
	v_mov_b32_e32 v57, v0
	v_mov_b32_e32 v58, v0
	v_mov_b32_e32 v59, v0
	v_mov_b32_e32 v60, v0
	v_mov_b32_e32 v61, v0
	v_mov_b32_e32 v62, v0
	v_mov_b32_e32 v63, v0
	v_mov_b32_e32 v64, v0
	v_mov_b32_e32 v65, v0
	v_mov_b32_e32 v66, v0
	v_mov_b32_e32 v67, v0
	v_mov_b32_e32 v68, v0
	v_mov_b32_e32 v69, v0
	v_mov_b32_e32 v70, v0
	v_mov_b32_e32 v71, v0
	v_mov_b32_e32 v72, v0
	v_mov_b32_e32 v73, v0
	v_mov_b32_e32 v74, v0
	v_mov_b32_e32 v75, v0
	v_mov_b32_e32 v76, v0
	v_mov_b32_e32 v77, v0
	v_mov_b32_e32 v78, v0
	v_mov_b32_e32 v79, v0
	v_mov_b32_e32 v96, v0
	v_mov_b32_e32 v97, v0
	v_mov_b32_e32 v98, v0
	v_mov_b32_e32 v99, v0
	v_mov_b32_e32 v100, v0
	v_mov_b32_e32 v101, v0
	v_mov_b32_e32 v102, v0
	v_mov_b32_e32 v103, v0
	v_mov_b32_e32 v104, v0
	v_mov_b32_e32 v105, v0
	v_mov_b32_e32 v106, v0
	v_mov_b32_e32 v107, v0
	v_mov_b32_e32 v108, v0
	v_mov_b32_e32 v109, v0
	v_mov_b32_e32 v110, v0
	v_mov_b32_e32 v111, v0
	v_mov_b32_e32 v80, v0
	v_mov_b32_e32 v81, v0
	v_mov_b32_e32 v82, v0
	v_mov_b32_e32 v83, v0
	v_mov_b32_e32 v84, v0
	v_mov_b32_e32 v85, v0
	v_mov_b32_e32 v86, v0
	v_mov_b32_e32 v87, v0
	v_mov_b32_e32 v88, v0
	v_mov_b32_e32 v89, v0
	v_mov_b32_e32 v90, v0
	v_mov_b32_e32 v91, v0
	v_mov_b32_e32 v92, v0
	v_mov_b32_e32 v93, v0
	v_mov_b32_e32 v94, v0
	v_mov_b32_e32 v95, v0
	v_mov_b32_e32 v112, v0
	v_mov_b32_e32 v113, v0
	v_mov_b32_e32 v114, v0
	v_mov_b32_e32 v115, v0
	v_mov_b32_e32 v116, v0
	v_mov_b32_e32 v117, v0
	v_mov_b32_e32 v118, v0
	v_mov_b32_e32 v119, v0
	v_mov_b32_e32 v120, v0
	v_mov_b32_e32 v121, v0
	v_mov_b32_e32 v122, v0
	v_mov_b32_e32 v123, v0
	v_mov_b32_e32 v124, v0
	v_mov_b32_e32 v125, v0
	v_mov_b32_e32 v126, v0
	v_mov_b32_e32 v127, v0
	.p2alignl 6, 3212836864
